# layer-1 weight transposes split over the idle WGs of layer-0 P4/P5/P6 tail rounds (shared out-of-line body)
# speedup vs baseline: 1.0392x; 1.0096x over previous
; #define LAS __attribute__((address_space(3)))
; #define TID() tid_now(wv)
; DEVI unsigned char* WSP() { return *(unsigned char* const __attribute__((address_space(4)))*)(kargs() + 8 * 22); }
; DEVI unsigned xb_add(unsigned* p, unsigned v) { return __hip_atomic_fetch_add(p, v, __ATOMIC_RELAXED, __HIP_MEMORY_SCOPE_AGENT); }
; DEVI unsigned xb_xcc_id() { return (unsigned)__builtin_amdgcn_s_getreg((3 << 11) | 20) & 0xFu; }
; #define WL(l, o) ((const bf16_t*)(WSP() + O_W + (size_t)(l) * W_LAYER + (o)))
; #define WSB(o) ((const bf16_t*)(WSP() + (o)))
; DEVI void grid_bar(int wv, LAS unsigned char* lds) {
;     asm volatile("s_waitcnt vmcnt(0)" ::: "memory");
;     __syncthreads();
;     if (TID() == 0) {
;         unsigned* bar = (unsigned*)(WSP() + O_CTL);
;         volatile LAS unsigned* st = (volatile LAS unsigned*)(lds + LDS_MISC);
;         const unsigned x = xb_xcc_id();
;         __builtin_amdgcn_s_waitcnt(0);
;         unsigned nloc = st[0], nx = st[1];
;         if (nloc == 0u) { xcd_barrier_complete(bar, x, nloc, nx); st[0] = nloc; st[1] = nx; }
;         const unsigned old = xb_add(&bar[XB_XSUB(x)], 1u);
;         const unsigned gen = old / nloc;
;         if (old + 1u == (gen + 1u) * nloc) {
; __global__ void __launch_bounds__(512, 2) fwd_kernel(Args args_unused) {
;     ...
;         { EpiGateA E{}; run_gemm(wv, lds, WSB(O_ATT), WL(l, W_A), 512, 512, MT, 1024, 512, off, E); }
;         grid_bar(wv, lds);
.LBB0_1468:
	s_waitcnt vmcnt(0) lgkmcnt(0)
	s_load_dword vcc_lo, s[0:1], 0xb8
	v_readlane_b32 vcc_hi, v255, 5
	s_waitcnt lgkmcnt(0)
	s_cmp_lg_u32 vcc_lo, 0x100
	s_cbranch_scc1 .Lsj_skip4
	s_sub_i32 vcc_hi, vcc_hi, 48
	s_and_b32 vcc_hi, vcc_hi, 0xff
	s_cmp_ge_u32 vcc_hi, 248
	s_cbranch_scc1 .Lsj_skip4
	v_readlane_b32 vcc_lo, v255, 0
	s_cmp_eq_u32 vcc_lo, 0
	s_cbranch_scc1 .Lsj_skip4
	v_writelane_b32 v201, s0, 0
	v_writelane_b32 v201, s1, 1
	v_writelane_b32 v201, s2, 2
	v_writelane_b32 v201, s3, 3
	v_writelane_b32 v201, s4, 4
	v_writelane_b32 v201, s5, 5
	v_writelane_b32 v201, s6, 6
	v_writelane_b32 v201, s7, 7
	v_writelane_b32 v201, s8, 8
	v_writelane_b32 v201, s9, 9
	v_writelane_b32 v201, s10, 10
	v_writelane_b32 v201, s11, 11
	v_writelane_b32 v201, s12, 12
	v_writelane_b32 v201, s13, 13
	v_writelane_b32 v201, s14, 14
	v_writelane_b32 v201, s15, 15
	v_writelane_b32 v201, s16, 16
	v_writelane_b32 v201, s17, 17
	v_writelane_b32 v201, s18, 18
	v_writelane_b32 v201, s19, 19
	v_writelane_b32 v201, s20, 20
	v_writelane_b32 v201, s21, 21
	v_writelane_b32 v201, s22, 22
	v_writelane_b32 v201, s23, 23
	v_writelane_b32 v201, s24, 24
	v_writelane_b32 v201, s25, 25
	v_writelane_b32 v201, s26, 26
	v_writelane_b32 v201, s27, 27
	v_writelane_b32 v201, s28, 28
	v_writelane_b32 v201, s29, 29
	v_writelane_b32 v201, s30, 30
	v_writelane_b32 v201, s31, 31
	v_writelane_b32 v201, s32, 32
	v_writelane_b32 v201, s33, 33
	v_writelane_b32 v201, s34, 34
	v_writelane_b32 v201, s35, 35
	v_writelane_b32 v201, s36, 36
	v_writelane_b32 v201, s37, 37
	v_writelane_b32 v201, s38, 38
	v_writelane_b32 v201, s39, 39
	v_writelane_b32 v201, s40, 40
	v_writelane_b32 v201, s41, 41
	v_writelane_b32 v201, s42, 42
	v_writelane_b32 v201, s43, 43
	v_writelane_b32 v201, s44, 44
	v_writelane_b32 v201, s45, 45
	v_writelane_b32 v201, s46, 46
	v_writelane_b32 v201, s47, 47
	v_writelane_b32 v201, s48, 48
	v_writelane_b32 v201, s49, 49
	v_writelane_b32 v201, s50, 50
	v_writelane_b32 v201, s51, 51
	v_writelane_b32 v201, s52, 52
	v_writelane_b32 v201, s53, 53
	v_writelane_b32 v201, s54, 54
	v_writelane_b32 v201, s55, 55
	v_writelane_b32 v201, s56, 56
	v_writelane_b32 v201, s57, 57
	v_writelane_b32 v201, s58, 58
	v_writelane_b32 v201, s59, 59
	v_writelane_b32 v201, s60, 60
	v_writelane_b32 v201, s61, 61
	v_writelane_b32 v201, s62, 62
	v_writelane_b32 v201, s63, 63
	v_writelane_b32 v202, s64, 0
	v_writelane_b32 v202, s65, 1
	v_writelane_b32 v202, s66, 2
	v_writelane_b32 v202, s67, 3
	v_writelane_b32 v202, s68, 4
	v_writelane_b32 v202, s69, 5
	v_writelane_b32 v202, s70, 6
	v_writelane_b32 v202, s71, 7
	v_writelane_b32 v202, s72, 8
	v_writelane_b32 v202, s73, 9
	v_writelane_b32 v202, s74, 10
	v_writelane_b32 v202, s75, 11
	v_writelane_b32 v202, s76, 12
	v_writelane_b32 v202, s77, 13
	v_writelane_b32 v202, s78, 14
	v_writelane_b32 v202, s79, 15
	v_writelane_b32 v202, s80, 16
	v_writelane_b32 v202, s81, 17
	v_writelane_b32 v202, s82, 18
	v_writelane_b32 v202, s83, 19
	v_writelane_b32 v202, s84, 20
	v_writelane_b32 v202, s85, 21
	v_writelane_b32 v202, s86, 22
	v_writelane_b32 v202, s87, 23
	v_writelane_b32 v202, s88, 24
	v_writelane_b32 v202, s89, 25
	v_writelane_b32 v202, s90, 26
	v_writelane_b32 v202, s91, 27
	v_writelane_b32 v202, s92, 28
	v_writelane_b32 v202, s93, 29
	v_writelane_b32 v202, s94, 30
	v_writelane_b32 v202, s95, 31
	v_writelane_b32 v202, s96, 32
	v_writelane_b32 v202, s97, 33
	v_writelane_b32 v202, s98, 34
	v_writelane_b32 v202, s99, 35
	v_mov_b32_e32 v200, v1
	s_mov_b32 s54, 0
	s_mov_b32 s52, -1
	s_cmp_lg_u32 vcc_lo, 0
	s_cbranch_scc0 .Lsj_par4
	s_mov_b32 s54, 6880
	s_mov_b32 s52, 8863
.Lsj_par4:
	s_mov_b32 s16, 248
	s_mov_b32 s18, vcc_hi
	s_mov_b32 s53, 4
	s_mov_b64 s[6:7], s[0:1]
	s_branch .Lsj_entry
.Lsj_ret4:
.Lsj_skip4:
	s_waitcnt vmcnt(0)
	s_barrier
	v_mbcnt_lo_u32_b32 v0, -1, 0
	v_mbcnt_hi_u32_b32 v0, -1, v0
	v_lshl_or_b32 v0, s33, 6, v0
	s_nop 0
	v_cmp_eq_u32_e32 vcc, 0, v0
	s_and_saveexec_b64 s[2:3], vcc
	s_cbranch_execz .LBB0_1520
	s_mov_b64 s[4:5], s[0:1]
	v_mov_b32_e32 v0, s80
	s_load_dwordx2 s[4:5], s[4:5], 0xb0
	s_getreg_b32 s6, hwreg(HW_REG_XCC_ID, 0, 4)
	s_waitcnt vmcnt(0) expcnt(0) lgkmcnt(0)
	ds_read_b32 v3, v0
	v_mov_b32_e32 v0, s81
	ds_read_b32 v0, v0
	s_and_b32 s12, s6, 15
	s_waitcnt lgkmcnt(1)
	v_cmp_ne_u32_e32 vcc, 0, v3
	s_cbranch_vccnz .LBB0_1484
	s_add_u32 s6, s4, 0x1000
	s_addc_u32 s7, s5, 0
	s_add_u32 s8, s4, 0x1100
	s_addc_u32 s9, s5, 0
	s_add_u32 s10, s4, 0x1200
	s_addc_u32 s11, s5, 0
	s_add_u32 s48, s4, 0x1300
	s_addc_u32 s49, s5, 0
	s_mov_b32 s15, 1
	s_branch .LBB0_1472

; DEVI const float* IN(int i) { return *(const float* const __attribute__((address_space(4)))*)(kargs() + 8 * i); }
; DEVI void prologue(int wv, LAS unsigned char* lds) {
;     ...
;     for (int it = gw; it < 2 * I_L; it += NGW) {
;         const int l = it / I_L; int r = it % I_L;
;         unsigned char* wl = ws + O_W + (size_t)l * W_LAYER;
;         if (r < I_IN) { const int kb = r / 101, nb = r % 101, n0 = nb * 32;
;             const int d0 = n0 < 384 ? n0 : n0 < 640 ? 512 + (n0 - 384) : n0 < 672 ? 384 + (n0 - 640) : n0 < 1184 ? 768 + (n0 - 672) : n0 < 2208 ? 1280 + (n0 - 1184) : 2304 + (n0 - 2208);
;             tr_item(IN(6) + (size_t)l * 1024 * 3232, 3232, 1024, IN(5) + l * 1024, (bf16_t*)(wl + W_IN), d0, scr, kb * 64, n0, lane); continue; }
;         r -= I_IN;
;         if (r < I_UQ) { const int kb = r / 24, nb = r % 24, n0 = nb * 32, hd = n0 / 96, dim0 = n0 % 96;
;             const int d0 = dim0 < 64 ? 256 * (hd >> 2) + 128 * (dim0 >> 5) + 32 * (hd & 3) : 512 + 128 * (hd >> 2) + 32 * (hd & 3);
;             tr_item(IN(9) + (size_t)l * 384 * 768, 768, 384, IN(7) + l * 384, (bf16_t*)(wl + W_UQ), d0, scr, kb * 64, n0, lane); continue; }
;         r -= I_UQ;
;         if (r < 2 * I_KV) { const int fold = r < I_KV; if (!fold) r -= I_KV;
;             const int kb = r / 32, nb = r % 32, n0 = nb * 32, hd = n0 / 128, dim0 = n0 % 128;
;             const bool isk = dim0 < 64;
;             const int d0 = isk ? 256 * (hd >> 2) + 128 * (dim0 >> 5) + 32 * (hd & 3) : hd * 64 + (dim0 - 64);
;             bf16_t* dst = (bf16_t*)(wl + (fold ? (isk ? W_K : W_V) : (isk ? W_KC : W_VC)));
;             tr_item(IN(10) + (size_t)l * 256 * 1024, 1024, 256, fold ? IN(8) + l * 256 : nullptr, dst, d0, scr, kb * 64, n0, lane); continue; }
;         r -= 2 * I_KV;
;         if (r < I_A) { tr_item(IN(13) + (size_t)l * 512 * 1024, 1024, 512, nullptr, (bf16_t*)(wl + W_A), (r % 32) * 32, scr, (r / 32) * 64, (r % 32) * 32, lane); continue; }
;         r -= I_A;
;         if (r < I_O) { tr_item(IN(17) + (size_t)l * 1024 * 1024, 1024, 1024, nullptr, (bf16_t*)(wl + W_O), (r % 32) * 32, scr, (r / 32) * 64, (r % 32) * 32, lane); continue; }
;         r -= I_O;
;         if (r < I_UP) { tr_item(IN(19) + (size_t)l * 1024 * 4096, 4096, 1024, IN(18) + l * 1024, (bf16_t*)(wl + W_UP), (r % 128) * 32, scr, (r / 128) * 64, (r % 128) * 32, lane); continue; }
;         r -= I_UP;
.LBB0_1559:
	s_waitcnt vmcnt(0) lgkmcnt(0)
	s_load_dword vcc_lo, s[0:1], 0xb8
	v_readlane_b32 vcc_hi, v255, 5
	s_waitcnt lgkmcnt(0)
	s_cmp_lg_u32 vcc_lo, 0x100
	s_cbranch_scc1 .Lsj_skip5
	s_sub_i32 vcc_hi, vcc_hi, 56
	s_and_b32 vcc_hi, vcc_hi, 0xff
	s_cmp_ge_u32 vcc_hi, 248
	s_cbranch_scc1 .Lsj_skip5
	v_readlane_b32 vcc_lo, v255, 0
	s_cmp_eq_u32 vcc_lo, 0
	s_cbranch_scc1 .Lsj_skip5
	v_writelane_b32 v201, s0, 0
	v_writelane_b32 v201, s1, 1
	v_writelane_b32 v201, s2, 2
	v_writelane_b32 v201, s3, 3
	v_writelane_b32 v201, s4, 4
	v_writelane_b32 v201, s5, 5
	v_writelane_b32 v201, s6, 6
	v_writelane_b32 v201, s7, 7
	v_writelane_b32 v201, s8, 8
	v_writelane_b32 v201, s9, 9
	v_writelane_b32 v201, s10, 10
	v_writelane_b32 v201, s11, 11
	v_writelane_b32 v201, s12, 12
	v_writelane_b32 v201, s13, 13
	v_writelane_b32 v201, s14, 14
	v_writelane_b32 v201, s15, 15
	v_writelane_b32 v201, s16, 16
	v_writelane_b32 v201, s17, 17
	v_writelane_b32 v201, s18, 18
	v_writelane_b32 v201, s19, 19
	v_writelane_b32 v201, s20, 20
	v_writelane_b32 v201, s21, 21
	v_writelane_b32 v201, s22, 22
	v_writelane_b32 v201, s23, 23
	v_writelane_b32 v201, s24, 24
	v_writelane_b32 v201, s25, 25
	v_writelane_b32 v201, s26, 26
	v_writelane_b32 v201, s27, 27
	v_writelane_b32 v201, s28, 28
	v_writelane_b32 v201, s29, 29
	v_writelane_b32 v201, s30, 30
	v_writelane_b32 v201, s31, 31
	v_writelane_b32 v201, s32, 32
	v_writelane_b32 v201, s33, 33
	v_writelane_b32 v201, s34, 34
	v_writelane_b32 v201, s35, 35
	v_writelane_b32 v201, s36, 36
	v_writelane_b32 v201, s37, 37
	v_writelane_b32 v201, s38, 38
	v_writelane_b32 v201, s39, 39
	v_writelane_b32 v201, s40, 40
	v_writelane_b32 v201, s41, 41
	v_writelane_b32 v201, s42, 42
	v_writelane_b32 v201, s43, 43
	v_writelane_b32 v201, s44, 44
	v_writelane_b32 v201, s45, 45
	v_writelane_b32 v201, s46, 46
	v_writelane_b32 v201, s47, 47
	v_writelane_b32 v201, s48, 48
	v_writelane_b32 v201, s49, 49
	v_writelane_b32 v201, s50, 50
	v_writelane_b32 v201, s51, 51
	v_writelane_b32 v201, s52, 52
	v_writelane_b32 v201, s53, 53
	v_writelane_b32 v201, s54, 54
	v_writelane_b32 v201, s55, 55
	v_writelane_b32 v201, s56, 56
	v_writelane_b32 v201, s57, 57
	v_writelane_b32 v201, s58, 58
	v_writelane_b32 v201, s59, 59
	v_writelane_b32 v201, s60, 60
	v_writelane_b32 v201, s61, 61
	v_writelane_b32 v201, s62, 62
	v_writelane_b32 v201, s63, 63
	v_writelane_b32 v202, s64, 0
	v_writelane_b32 v202, s65, 1
	v_writelane_b32 v202, s66, 2
	v_writelane_b32 v202, s67, 3
	v_writelane_b32 v202, s68, 4
	v_writelane_b32 v202, s69, 5
	v_writelane_b32 v202, s70, 6
	v_writelane_b32 v202, s71, 7
	v_writelane_b32 v202, s72, 8
	v_writelane_b32 v202, s73, 9
	v_writelane_b32 v202, s74, 10
	v_writelane_b32 v202, s75, 11
	v_writelane_b32 v202, s76, 12
	v_writelane_b32 v202, s77, 13
	v_writelane_b32 v202, s78, 14
	v_writelane_b32 v202, s79, 15
	v_writelane_b32 v202, s80, 16
	v_writelane_b32 v202, s81, 17
	v_writelane_b32 v202, s82, 18
	v_writelane_b32 v202, s83, 19
	v_writelane_b32 v202, s84, 20
	v_writelane_b32 v202, s85, 21
	v_writelane_b32 v202, s86, 22
	v_writelane_b32 v202, s87, 23
	v_writelane_b32 v202, s88, 24
	v_writelane_b32 v202, s89, 25
	v_writelane_b32 v202, s90, 26
	v_writelane_b32 v202, s91, 27
	v_writelane_b32 v202, s92, 28
	v_writelane_b32 v202, s93, 29
	v_writelane_b32 v202, s94, 30
	v_writelane_b32 v202, s95, 31
	v_writelane_b32 v202, s96, 32
	v_writelane_b32 v202, s97, 33
	v_writelane_b32 v202, s98, 34
	v_writelane_b32 v202, s99, 35
	v_mov_b32_e32 v200, v1
	s_mov_b32 s54, 0
	s_mov_b32 s52, -1
	s_cmp_lg_u32 vcc_lo, 0
	s_cbranch_scc0 .Lsj_par5
	s_mov_b32 s54, 8864
	s_mov_b32 s52, 12831
; #define LAS __attribute__((address_space(3)))
; #define TID() tid_now(wv)
; #define BID() opq_s((int)blockIdx.x)
; #define GDIM() opq_s((int)gridDim.x)
; DEVI const float* IN(int i) { return *(const float* const __attribute__((address_space(4)))*)(kargs() + 8 * i); }
; DEVI unsigned char* WSP() { return *(unsigned char* const __attribute__((address_space(4)))*)(kargs() + 8 * 22); }
; DEVI void prologue(int wv, LAS unsigned char* lds) {
;     const int tid = TID(), lane = tid & 63, wave = __builtin_amdgcn_readfirstlane(tid >> 6);
;     const int G = GDIM(), bx = BID();
;     const int gw = bx * 8 + wave, NGW = G * 8;
;     const size_t gt = (size_t)bx * 512 + tid, NGT = (size_t)G * 512;
;     unsigned char* ws = WSP();
;     LAS float* scr = (LAS float*)(lds + wave * 8448);
;     constexpr int I_IN = 16 * 101, I_UQ = 6 * 24, I_KV = 4 * 32, I_A = 8 * 32, I_O = 16 * 32, I_UP = 16 * 128, I_DN = 64 * 32;
;     constexpr int I_L = I_IN + I_UQ + 2 * I_KV + I_A + I_O + I_UP + I_DN;
;     for (int it = gw; it < 2 * I_L; it += NGW) {
;         const int l = it / I_L; int r = it % I_L;
;         unsigned char* wl = ws + O_W + (size_t)l * W_LAYER;
;         if (r < I_IN) { const int kb = r / 101, nb = r % 101, n0 = nb * 32;
;             const int d0 = n0 < 384 ? n0 : n0 < 640 ? 512 + (n0 - 384) : n0 < 672 ? 384 + (n0 - 640) : n0 < 1184 ? 768 + (n0 - 672) : n0 < 2208 ? 1280 + (n0 - 1184) : 2304 + (n0 - 2208);
;             tr_item(IN(6) + (size_t)l * 1024 * 3232, 3232, 1024, IN(5) + l * 1024, (bf16_t*)(wl + W_IN), d0, scr, kb * 64, n0, lane); continue; }
.Lsj_par5:
	s_mov_b32 s16, 248
	s_mov_b32 s18, vcc_hi
	s_mov_b32 s53, 5
	s_mov_b64 s[6:7], s[0:1]
.Lsj_entry:
	v_mbcnt_lo_u32_b32 v64, -1, 0
	v_mbcnt_hi_u32_b32 v64, -1, v64
	v_lshl_or_b32 v64, s33, 6, v64
	s_load_dwordx2 s[20:21], s[6:7], 0xb0
	v_readfirstlane_b32 s2, v64
	s_ashr_i32 s2, s2, 6
	s_lshl_b32 s3, s18, 3
	v_and_b32_e32 v34, 63, v64
	s_add_i32 s4, s3, s2
	s_add_i32 s4, s4, s54
	s_lshl_b32 s14, s16, 3
	s_ashr_i32 s17, s16, 31
	v_ashrrev_i32_e32 v65, 31, v64
	s_cmp_gt_i32 s4, s52
	v_lshlrev_b32_e32 v66, 3, v34
	s_cbranch_scc1 .Lsj_end
	v_lshrrev_b32_e32 v0, 5, v34
	s_movk_i32 s3, 0x84
	v_mov_b32_e32 v1, 0x108
	v_mad_u32_u24 v13, v0, s3, v1
	v_mov_b32_e32 v1, 0x210
	v_mad_u32_u24 v15, v0, s3, v1
	v_mov_b32_e32 v1, 0x318
	v_mad_u32_u24 v17, v0, s3, v1
	v_mov_b32_e32 v1, 0x420
	v_mad_u32_u24 v19, v0, s3, v1
	v_mov_b32_e32 v1, 0x528
	v_mad_u32_u24 v21, v0, s3, v1
	v_mov_b32_e32 v1, 0x630
	v_mad_u32_u24 v23, v0, s3, v1
	v_mov_b32_e32 v1, 0x738
	v_mad_u32_u24 v25, v0, s3, v1
	v_mov_b32_e32 v1, 0x840
	v_mad_u32_u24 v27, v0, s3, v1
	v_mov_b32_e32 v1, 0x948
	v_mad_u32_u24 v29, v0, s3, v1
	v_mov_b32_e32 v1, 0xa50
	v_mad_u32_u24 v31, v0, s3, v1
	v_mov_b32_e32 v1, 0xb58
	v_mad_u32_u24 v33, v0, s3, v1
	v_mov_b32_e32 v1, 0xc60
	v_mad_u32_u24 v36, v0, s3, v1
	v_mov_b32_e32 v1, 0xd68
	v_mad_u32_u24 v38, v0, s3, v1
	v_mov_b32_e32 v1, 0xe70
	v_mad_u32_u24 v40, v0, s3, v1
	v_mov_b32_e32 v1, 0xf78
	v_mad_u32_u24 v42, v0, s3, v1
	v_mov_b32_e32 v1, 0x1080
	v_mad_u32_u24 v44, v0, s3, v1
	v_mov_b32_e32 v1, 0x1188
	v_mad_u32_u24 v46, v0, s3, v1
	v_mov_b32_e32 v1, 0x1290
	v_mad_u32_u24 v48, v0, s3, v1
	v_mov_b32_e32 v1, 0x1398
	v_mad_u32_u24 v50, v0, s3, v1
	v_mov_b32_e32 v1, 0x14a0
	v_mad_u32_u24 v51, v0, s3, v1
	v_mov_b32_e32 v1, 0x15a8
	v_mad_u32_u24 v52, v0, s3, v1
	v_mov_b32_e32 v1, 0x16b0
	s_mulk_i32 s2, 0x2100
	v_mad_u32_u24 v53, v0, s3, v1
	v_mov_b32_e32 v1, 0x17b8
	v_lshrrev_b32_e32 v55, 3, v34
	v_and_b32_e32 v6, 56, v66
	s_add_i32 s2, s2, 0
	v_mad_u32_u24 v54, v0, s3, v1
	v_mul_u32_u24_e32 v1, 0x84, v6
	v_lshlrev_b32_e32 v4, 2, v55
	s_waitcnt lgkmcnt(0)
	s_add_u32 s5, s20, 0x390800
	v_and_b32_e32 v2, 31, v64
	v_mov_b32_e32 v5, 0
	v_add3_u32 v56, s2, v1, v4
	v_mov_b32_e32 v1, 0x18c0
	s_mov_b32 s7, 0
	s_addc_u32 s15, s21, 0
	v_lshl_add_u32 v3, v2, 2, s2
	v_mul_u32_u24_e32 v7, 0x84, v0
	v_or_b32_e32 v12, 2, v0
	v_or_b32_e32 v14, 4, v0
	v_or_b32_e32 v16, 6, v0
	v_or_b32_e32 v18, 8, v0
	v_or_b32_e32 v20, 10, v0
	v_or_b32_e32 v22, 12, v0
	v_or_b32_e32 v24, 14, v0
	v_or_b32_e32 v26, 16, v0
	v_or_b32_e32 v28, 18, v0
	v_or_b32_e32 v30, 20, v0
	v_or_b32_e32 v32, 22, v0
	v_or_b32_e32 v35, 24, v0
	v_or_b32_e32 v37, 26, v0
	v_or_b32_e32 v39, 28, v0
	v_or_b32_e32 v41, 30, v0
	v_or_b32_e32 v43, 32, v0
	v_or_b32_e32 v45, 34, v0
	v_or_b32_e32 v47, 36, v0
	v_or_b32_e32 v49, 38, v0
	v_mad_u32_u24 v57, v0, s3, v1
	v_mov_b32_e32 v1, v5
	s_lshl_b32 s19, s4, 1
	s_lshl_b32 s40, s16, 4
	s_lshl_b32 s41, s4, 5
	s_lshl_b32 s42, s16, 8
	s_mov_b64 s[8:9], 0x1410000
	s_mov_b64 s[10:11], 0xc10000
	s_mov_b64 s[12:13], 0xa10000
	s_mov_b64 s[22:23], 0x810000
	s_movk_i32 s43, 0xf920
	s_movk_i32 s44, 0x300
	s_movk_i32 s45, 0xc00
	s_mov_b64 s[24:25], 0x680000
	s_mov_b32 s46, s4
	v_or_b32_e32 v58, 40, v0
	v_or_b32_e32 v59, 42, v0
	v_or_b32_e32 v60, 44, v0
	v_or_b32_e32 v61, 46, v0
	v_or_b32_e32 v62, 48, v0
	v_or_b32_e32 v63, 50, v0
	v_or_b32_e32 v67, 52, v0
	v_or_b32_e32 v68, 54, v0
	v_or_b32_e32 v69, 56, v0
	v_or_b32_e32 v70, 58, v0
	v_or_b32_e32 v71, 60, v0
	v_or_b32_e32 v72, 62, v0
	v_or_b32_e32 v73, 8, v55
	v_or_b32_e32 v74, 16, v55
	v_or_b32_e32 v75, 24, v55
	s_branch .Lsj_28

; DEVI const float* IN(int i) { return *(const float* const __attribute__((address_space(4)))*)(kargs() + 8 * i); }
; DEVI void prologue(int wv, LAS unsigned char* lds) {
;     ...
;     for (int it = gw; it < 2 * I_L; it += NGW) {
;         const int l = it / I_L; int r = it % I_L;
;         unsigned char* wl = ws + O_W + (size_t)l * W_LAYER;
;         if (r < I_IN) { const int kb = r / 101, nb = r % 101, n0 = nb * 32;
;             const int d0 = n0 < 384 ? n0 : n0 < 640 ? 512 + (n0 - 384) : n0 < 672 ? 384 + (n0 - 640) : n0 < 1184 ? 768 + (n0 - 672) : n0 < 2208 ? 1280 + (n0 - 1184) : 2304 + (n0 - 2208);
;             tr_item(IN(6) + (size_t)l * 1024 * 3232, 3232, 1024, IN(5) + l * 1024, (bf16_t*)(wl + W_IN), d0, scr, kb * 64, n0, lane); continue; }
;         r -= I_IN;
;         if (r < I_UQ) { const int kb = r / 24, nb = r % 24, n0 = nb * 32, hd = n0 / 96, dim0 = n0 % 96;
;             const int d0 = dim0 < 64 ? 256 * (hd >> 2) + 128 * (dim0 >> 5) + 32 * (hd & 3) : 512 + 128 * (hd >> 2) + 32 * (hd & 3);
;             tr_item(IN(9) + (size_t)l * 384 * 768, 768, 384, IN(7) + l * 384, (bf16_t*)(wl + W_UQ), d0, scr, kb * 64, n0, lane); continue; }
;         r -= I_UQ;
;         if (r < 2 * I_KV) { const int fold = r < I_KV; if (!fold) r -= I_KV;
;             const int kb = r / 32, nb = r % 32, n0 = nb * 32, hd = n0 / 128, dim0 = n0 % 128;
;             const bool isk = dim0 < 64;
;             const int d0 = isk ? 256 * (hd >> 2) + 128 * (dim0 >> 5) + 32 * (hd & 3) : hd * 64 + (dim0 - 64);
;             bf16_t* dst = (bf16_t*)(wl + (fold ? (isk ? W_K : W_V) : (isk ? W_KC : W_VC)));
;             tr_item(IN(10) + (size_t)l * 256 * 1024, 1024, 256, fold ? IN(8) + l * 256 : nullptr, dst, d0, scr, kb * 64, n0, lane); continue; }
;         r -= 2 * I_KV;
;         if (r < I_A) { tr_item(IN(13) + (size_t)l * 512 * 1024, 1024, 512, nullptr, (bf16_t*)(wl + W_A), (r % 32) * 32, scr, (r / 32) * 64, (r % 32) * 32, lane); continue; }
;         r -= I_A;
;         if (r < I_O) { tr_item(IN(17) + (size_t)l * 1024 * 1024, 1024, 1024, nullptr, (bf16_t*)(wl + W_O), (r % 32) * 32, scr, (r / 32) * 64, (r % 32) * 32, lane); continue; }
;         r -= I_O;
;         if (r < I_UP) { tr_item(IN(19) + (size_t)l * 1024 * 4096, 4096, 1024, IN(18) + l * 1024, (bf16_t*)(wl + W_UP), (r % 128) * 32, scr, (r / 128) * 64, (r % 128) * 32, lane); continue; }
;         r -= I_UP;
.Lsj_end:
	s_mov_b64 exec, -1
	s_waitcnt lgkmcnt(0)
	s_mov_b32 vcc_lo, s53
	v_mov_b32_e32 v1, v200
	v_readlane_b32 s0, v201, 0
	v_readlane_b32 s1, v201, 1
	v_readlane_b32 s2, v201, 2
	v_readlane_b32 s3, v201, 3
	v_readlane_b32 s4, v201, 4
	v_readlane_b32 s5, v201, 5
	v_readlane_b32 s6, v201, 6
	v_readlane_b32 s7, v201, 7
	v_readlane_b32 s8, v201, 8
	v_readlane_b32 s9, v201, 9
	v_readlane_b32 s10, v201, 10
	v_readlane_b32 s11, v201, 11
	v_readlane_b32 s12, v201, 12
	v_readlane_b32 s13, v201, 13
	v_readlane_b32 s14, v201, 14
	v_readlane_b32 s15, v201, 15
	v_readlane_b32 s16, v201, 16
	v_readlane_b32 s17, v201, 17
	v_readlane_b32 s18, v201, 18
	v_readlane_b32 s19, v201, 19
	v_readlane_b32 s20, v201, 20
	v_readlane_b32 s21, v201, 21
	v_readlane_b32 s22, v201, 22
	v_readlane_b32 s23, v201, 23
	v_readlane_b32 s24, v201, 24
	v_readlane_b32 s25, v201, 25
	v_readlane_b32 s26, v201, 26
	v_readlane_b32 s27, v201, 27
	v_readlane_b32 s28, v201, 28
	v_readlane_b32 s29, v201, 29
	v_readlane_b32 s30, v201, 30
	v_readlane_b32 s31, v201, 31
	v_readlane_b32 s32, v201, 32
	v_readlane_b32 s33, v201, 33
	v_readlane_b32 s34, v201, 34
	v_readlane_b32 s35, v201, 35
	v_readlane_b32 s36, v201, 36
	v_readlane_b32 s37, v201, 37
	v_readlane_b32 s38, v201, 38
	v_readlane_b32 s39, v201, 39
	v_readlane_b32 s40, v201, 40
	v_readlane_b32 s41, v201, 41
	v_readlane_b32 s42, v201, 42
	v_readlane_b32 s43, v201, 43
	v_readlane_b32 s44, v201, 44
	v_readlane_b32 s45, v201, 45
	v_readlane_b32 s46, v201, 46
	v_readlane_b32 s47, v201, 47
	v_readlane_b32 s48, v201, 48
	v_readlane_b32 s49, v201, 49
	v_readlane_b32 s50, v201, 50
	v_readlane_b32 s51, v201, 51
	v_readlane_b32 s52, v201, 52
	v_readlane_b32 s53, v201, 53
	v_readlane_b32 s54, v201, 54
	v_readlane_b32 s55, v201, 55
	v_readlane_b32 s56, v201, 56
	v_readlane_b32 s57, v201, 57
	v_readlane_b32 s58, v201, 58
	v_readlane_b32 s59, v201, 59
	v_readlane_b32 s60, v201, 60
	v_readlane_b32 s61, v201, 61
	v_readlane_b32 s62, v201, 62
	v_readlane_b32 s63, v201, 63
	v_readlane_b32 s64, v202, 0
	v_readlane_b32 s65, v202, 1
	v_readlane_b32 s66, v202, 2
	v_readlane_b32 s67, v202, 3
	v_readlane_b32 s68, v202, 4
	v_readlane_b32 s69, v202, 5
	v_readlane_b32 s70, v202, 6
	v_readlane_b32 s71, v202, 7
	v_readlane_b32 s72, v202, 8
	v_readlane_b32 s73, v202, 9
	v_readlane_b32 s74, v202, 10
	v_readlane_b32 s75, v202, 11
	v_readlane_b32 s76, v202, 12
	v_readlane_b32 s77, v202, 13
	v_readlane_b32 s78, v202, 14
	v_readlane_b32 s79, v202, 15
	v_readlane_b32 s80, v202, 16
	v_readlane_b32 s81, v202, 17
	v_readlane_b32 s82, v202, 18
	v_readlane_b32 s83, v202, 19
	v_readlane_b32 s84, v202, 20
	v_readlane_b32 s85, v202, 21
	v_readlane_b32 s86, v202, 22
	v_readlane_b32 s87, v202, 23
	v_readlane_b32 s88, v202, 24
	v_readlane_b32 s89, v202, 25
	v_readlane_b32 s90, v202, 26
	v_readlane_b32 s91, v202, 27
	v_readlane_b32 s92, v202, 28
	v_readlane_b32 s93, v202, 29
	v_readlane_b32 s94, v202, 30
	v_readlane_b32 s95, v202, 31
	v_readlane_b32 s96, v202, 32
	v_readlane_b32 s97, v202, 33
	v_readlane_b32 s98, v202, 34
	v_readlane_b32 s99, v202, 35
	s_nop 7
	s_cmp_eq_u32 vcc_lo, 4
	s_cbranch_scc1 .Lsj_ret4
	s_cmp_eq_u32 vcc_lo, 6
	s_cbranch_scc1 .Lsj_ret6

; #define LAS __attribute__((address_space(3)))
; #define TID() tid_now(wv)
; DEVI unsigned char* WSP() { return *(unsigned char* const __attribute__((address_space(4)))*)(kargs() + 8 * 22); }
; DEVI unsigned xb_add(unsigned* p, unsigned v) { return __hip_atomic_fetch_add(p, v, __ATOMIC_RELAXED, __HIP_MEMORY_SCOPE_AGENT); }
; DEVI unsigned xb_xcc_id() { return (unsigned)__builtin_amdgcn_s_getreg((3 << 11) | 20) & 0xFu; }
; #define WL(l, o) ((const bf16_t*)(WSP() + O_W + (size_t)(l) * W_LAYER + (o)))
; #define WSB(o) ((const bf16_t*)(WSP() + (o)))
; DEVI void grid_bar(int wv, LAS unsigned char* lds) {
;     asm volatile("s_waitcnt vmcnt(0)" ::: "memory");
;     __syncthreads();
;     if (TID() == 0) {
;         unsigned* bar = (unsigned*)(WSP() + O_CTL);
;         volatile LAS unsigned* st = (volatile LAS unsigned*)(lds + LDS_MISC);
;         const unsigned x = xb_xcc_id();
;         __builtin_amdgcn_s_waitcnt(0);
;         unsigned nloc = st[0], nx = st[1];
;         if (nloc == 0u) { xcd_barrier_complete(bar, x, nloc, nx); st[0] = nloc; st[1] = nx; }
;         const unsigned old = xb_add(&bar[XB_XSUB(x)], 1u);
;         const unsigned gen = old / nloc;
;         if (old + 1u == (gen + 1u) * nloc) {
; __global__ void __launch_bounds__(512, 2) fwd_kernel(Args args_unused) {
;     ...
;         { EpiUp E{l}; run_gemm(wv, lds, WSB(O_XB), WL(l, W_UP), 1024, 1024, MT, DFF, 1024, off, E); }
;         grid_bar(wv, lds);
.LBB0_1627:
	s_waitcnt vmcnt(0) lgkmcnt(0)
	s_load_dword vcc_lo, s[0:1], 0xb8
	v_readlane_b32 vcc_hi, v255, 5
	s_waitcnt lgkmcnt(0)
	s_cmp_lg_u32 vcc_lo, 0x100
	s_cbranch_scc1 .Lsj_skip6
	s_sub_i32 vcc_hi, vcc_hi, 88
	s_and_b32 vcc_hi, vcc_hi, 0xff
	s_cmp_ge_u32 vcc_hi, 224
	s_cbranch_scc1 .Lsj_skip6
	v_readlane_b32 vcc_lo, v255, 0
	s_cmp_eq_u32 vcc_lo, 0
	s_cbranch_scc1 .Lsj_skip6
	v_writelane_b32 v201, s0, 0
	v_writelane_b32 v201, s1, 1
	v_writelane_b32 v201, s2, 2
	v_writelane_b32 v201, s3, 3
	v_writelane_b32 v201, s4, 4
	v_writelane_b32 v201, s5, 5
	v_writelane_b32 v201, s6, 6
	v_writelane_b32 v201, s7, 7
	v_writelane_b32 v201, s8, 8
	v_writelane_b32 v201, s9, 9
	v_writelane_b32 v201, s10, 10
	v_writelane_b32 v201, s11, 11
	v_writelane_b32 v201, s12, 12
	v_writelane_b32 v201, s13, 13
	v_writelane_b32 v201, s14, 14
	v_writelane_b32 v201, s15, 15
	v_writelane_b32 v201, s16, 16
	v_writelane_b32 v201, s17, 17
	v_writelane_b32 v201, s18, 18
	v_writelane_b32 v201, s19, 19
	v_writelane_b32 v201, s20, 20
	v_writelane_b32 v201, s21, 21
	v_writelane_b32 v201, s22, 22
	v_writelane_b32 v201, s23, 23
	v_writelane_b32 v201, s24, 24
	v_writelane_b32 v201, s25, 25
	v_writelane_b32 v201, s26, 26
	v_writelane_b32 v201, s27, 27
	v_writelane_b32 v201, s28, 28
	v_writelane_b32 v201, s29, 29
	v_writelane_b32 v201, s30, 30
	v_writelane_b32 v201, s31, 31
	v_writelane_b32 v201, s32, 32
	v_writelane_b32 v201, s33, 33
	v_writelane_b32 v201, s34, 34
	v_writelane_b32 v201, s35, 35
	v_writelane_b32 v201, s36, 36
	v_writelane_b32 v201, s37, 37
	v_writelane_b32 v201, s38, 38
	v_writelane_b32 v201, s39, 39
	v_writelane_b32 v201, s40, 40
	v_writelane_b32 v201, s41, 41
	v_writelane_b32 v201, s42, 42
	v_writelane_b32 v201, s43, 43
	v_writelane_b32 v201, s44, 44
	v_writelane_b32 v201, s45, 45
	v_writelane_b32 v201, s46, 46
	v_writelane_b32 v201, s47, 47
	v_writelane_b32 v201, s48, 48
	v_writelane_b32 v201, s49, 49
	v_writelane_b32 v201, s50, 50
	v_writelane_b32 v201, s51, 51
	v_writelane_b32 v201, s52, 52
	v_writelane_b32 v201, s53, 53
	v_writelane_b32 v201, s54, 54
	v_writelane_b32 v201, s55, 55
	v_writelane_b32 v201, s56, 56
	v_writelane_b32 v201, s57, 57
	v_writelane_b32 v201, s58, 58
	v_writelane_b32 v201, s59, 59
	v_writelane_b32 v201, s60, 60
	v_writelane_b32 v201, s61, 61
	v_writelane_b32 v201, s62, 62
	v_writelane_b32 v201, s63, 63
	v_writelane_b32 v202, s64, 0
	v_writelane_b32 v202, s65, 1
	v_writelane_b32 v202, s66, 2
	v_writelane_b32 v202, s67, 3
	v_writelane_b32 v202, s68, 4
	v_writelane_b32 v202, s69, 5
	v_writelane_b32 v202, s70, 6
	v_writelane_b32 v202, s71, 7
	v_writelane_b32 v202, s72, 8
	v_writelane_b32 v202, s73, 9
	v_writelane_b32 v202, s74, 10
	v_writelane_b32 v202, s75, 11
	v_writelane_b32 v202, s76, 12
	v_writelane_b32 v202, s77, 13
	v_writelane_b32 v202, s78, 14
	v_writelane_b32 v202, s79, 15
	v_writelane_b32 v202, s80, 16
	v_writelane_b32 v202, s81, 17
	v_writelane_b32 v202, s82, 18
	v_writelane_b32 v202, s83, 19
	v_writelane_b32 v202, s84, 20
	v_writelane_b32 v202, s85, 21
	v_writelane_b32 v202, s86, 22
	v_writelane_b32 v202, s87, 23
	v_writelane_b32 v202, s88, 24
	v_writelane_b32 v202, s89, 25
	v_writelane_b32 v202, s90, 26
	v_writelane_b32 v202, s91, 27
	v_writelane_b32 v202, s92, 28
	v_writelane_b32 v202, s93, 29
	v_writelane_b32 v202, s94, 30
	v_writelane_b32 v202, s95, 31
	v_writelane_b32 v202, s96, 32
	v_writelane_b32 v202, s97, 33
	v_writelane_b32 v202, s98, 34
	v_writelane_b32 v202, s99, 35
	v_mov_b32_e32 v200, v1
	s_mov_b32 s54, 0
	s_mov_b32 s52, -1
	s_cmp_lg_u32 vcc_lo, 0
	s_cbranch_scc0 .Lsj_par6
	s_mov_b32 s54, 12832
	s_mov_b32 s52, 13759
.Lsj_par6:
	s_mov_b32 s16, 224
	s_mov_b32 s18, vcc_hi
	s_mov_b32 s53, 6
	s_mov_b64 s[6:7], s[0:1]
	s_branch .Lsj_entry
.Lsj_ret6:
.Lsj_skip6:
	s_waitcnt vmcnt(0)
	s_barrier
	v_mbcnt_lo_u32_b32 v0, -1, 0
	v_mbcnt_hi_u32_b32 v0, -1, v0
	v_lshl_or_b32 v0, s33, 6, v0
	s_nop 0
	v_cmp_eq_u32_e32 vcc, 0, v0
	s_and_saveexec_b64 s[2:3], vcc
	s_cbranch_execz .LBB0_1679
	s_mov_b64 s[4:5], s[0:1]
	v_mov_b32_e32 v0, s80
	s_load_dwordx2 s[4:5], s[4:5], 0xb0
	s_getreg_b32 s6, hwreg(HW_REG_XCC_ID, 0, 4)
	s_waitcnt vmcnt(0) expcnt(0) lgkmcnt(0)
	ds_read_b32 v3, v0
	v_mov_b32_e32 v0, s81
	ds_read_b32 v0, v0
	s_and_b32 s12, s6, 15
	s_waitcnt lgkmcnt(1)
	v_cmp_ne_u32_e32 vcc, 0, v3
	s_cbranch_vccnz .LBB0_1643
	s_add_u32 s6, s4, 0x1000
	s_addc_u32 s7, s5, 0
	s_add_u32 s8, s4, 0x1100
	s_addc_u32 s9, s5, 0
	s_add_u32 s10, s4, 0x1200
	s_addc_u32 s11, s5, 0
	s_add_u32 s46, s4, 0x1300
	s_addc_u32 s47, s5, 0
	s_mov_b32 s15, 1
	s_branch .LBB0_1631
